# rec_pass1 prologue LDS loops (prefix add, decayed keys, GLA group prefix): all reads issued together, one wait, same arithmetic order
# speedup vs baseline: 1.0089x; 1.0089x over previous
.LBB0_190:
	s_cmpk_gt_i32 s20, 0xff
	s_mov_b64 s[2:3], -1
	s_cbranch_scc0 .LBB0_292
	s_lshl_b32 s6, s20, 1
	s_cmpk_gt_u32 s20, 0x2ff
	s_cbranch_scc0 .LBB0_231
	v_mov_b32_e32 v0, v206
	s_add_i32 s2, s6, 0xfffffa00
	v_ashrrev_i32_e32 v0, 8, v0
	v_mov_b32_e32 v106, v206
	v_mov_b32_e32 v111, v206
	v_add_u32_e32 v102, s2, v0
	v_mov_b32_e32 v1, v206
	v_bfe_u32 v2, v111, 6, 2
	s_movk_i32 s2, 0x100
	v_ashrrev_i32_e32 v0, 9, v102
	v_xor_b32_e32 v3, 3, v2
	v_cmp_gt_u32_e32 vcc, s2, v1
	v_ashrrev_i32_e32 v1, 31, v0
	v_and_b32_e32 v107, 15, v111
	v_cndmask_b32_e32 v108, v3, v2, vcc
	v_lshlrev_b64 v[100:101], 13, v[0:1]
	v_lshlrev_b32_e32 v0, 6, v102
	s_movk_i32 s2, 0x1fc0
	v_lshlrev_b32_e32 v113, 4, v108
	v_and_or_b32 v12, v0, s2, v100
	v_or_b32_e32 v110, v113, v107
	v_or_b32_e32 v100, v12, v110
	v_mov_b64_e32 v[0:1], s[68:69]
	v_bfe_u32 v8, v102, 7, 2
	v_mad_u64_u32 v[0:1], s[2:3], v100, s13, v[0:1]
	v_bfe_u32 v112, v111, 4, 2
	v_mad_i32_i24 v1, v101, s13, v1
	v_lshlrev_b32_e32 v176, 6, v8
	v_lshl_add_u64 v[0:1], v[0:1], 0, v[176:177]
	v_lshlrev_b32_e32 v2, 4, v112
	v_mov_b32_e32 v3, v177
	v_lshl_add_u64 v[0:1], v[0:1], 0, v[2:3]
	s_mov_b32 s2, 0x3e80000
	v_add_co_u32_e32 v0, vcc, s2, v0
	v_mov_b32_e32 v115, v206
	s_nop 0
	v_addc_co_u32_e32 v1, vcc, 0, v1, vcc
	global_load_dwordx4 v[0:3], v[0:1], off offset:3584
	v_lshlrev_b32_e32 v104, 7, v8
	v_bfe_u32 v116, v115, 2, 6
	v_lshlrev_b32_e32 v4, 4, v115
	v_and_b32_e32 v117, 48, v4
	v_or_b32_e32 v6, v12, v116
	v_mov_b64_e32 v[4:5], s[76:77]
	v_bfe_u32 v103, v115, 5, 3
	v_mad_u64_u32 v[6:7], s[2:3], v6, s13, v[4:5]
	v_mad_i32_i24 v7, v101, s13, v7
	v_mov_b32_e32 v105, v177
	v_lshlrev_b32_e32 v114, 3, v103
	v_lshlrev_b32_e32 v109, 5, v8
	v_lshl_add_u64 v[6:7], v[6:7], 0, v[104:105]
	v_lshlrev_b32_e32 v8, 1, v117
	v_mov_b32_e32 v9, v177
	v_or_b32_e32 v167, 1, v114
	v_lshl_add_u64 v[6:7], v[6:7], 0, v[8:9]
	s_mov_b64 s[2:3], 0x1000
	v_or_b32_e32 v8, v114, v12
	v_or_b32_e32 v12, v12, v167
	v_mov_b32_e32 v13, v101
	v_lshl_add_u64 v[158:159], v[6:7], 0, s[2:3]
	v_lshlrev_b64 v[14:15], 6, v[12:13]
	v_mad_u64_u32 v[12:13], s[2:3], v12, s13, v[4:5]
	v_and_b32_e32 v166, 31, v115
	v_mov_b32_e32 v9, v101
	v_readlane_b32 s4, v254, 15
	v_mad_i32_i24 v13, v101, s13, v13
	v_lshlrev_b64 v[10:11], 6, v[8:9]
	v_readlane_b32 s5, v254, 16
	v_lshlrev_b32_e32 v40, 1, v166
	v_mov_b32_e32 v41, v177
	v_lshl_add_u64 v[12:13], v[12:13], 0, v[176:177]
	v_lshl_add_u64 v[154:155], s[4:5], 0, v[10:11]
	v_lshl_add_u64 v[14:15], s[4:5], 0, v[14:15]
	v_lshl_add_u64 v[42:43], v[12:13], 0, v[40:41]
	v_or_b32_e32 v12, 2, v8
	v_mov_b32_e32 v13, v101
	global_load_dwordx4 v[118:121], v[154:155], off offset:32
	global_load_dwordx4 v[122:125], v[154:155], off offset:16
	global_load_dwordx4 v[126:129], v[14:15], off offset:48
	global_load_dwordx4 v[130:133], v[14:15], off offset:32
	global_load_dwordx4 v[134:137], v[14:15], off offset:16
	global_load_dwordx4 v[138:141], v[14:15], off
	v_lshlrev_b64 v[14:15], 6, v[12:13]
	v_mad_u64_u32 v[12:13], s[2:3], v12, s13, v[4:5]
	v_mad_i32_i24 v13, v101, s13, v13
	v_lshl_add_u64 v[12:13], v[12:13], 0, v[176:177]
	v_lshl_add_u64 v[58:59], v[12:13], 0, v[40:41]
	v_or_b32_e32 v12, 3, v8
	v_mov_b32_e32 v13, v101
	v_lshl_add_u64 v[56:57], s[4:5], 0, v[14:15]
	v_lshlrev_b64 v[14:15], 6, v[12:13]
	v_mad_u64_u32 v[12:13], s[2:3], v12, s13, v[4:5]
	v_mad_i32_i24 v13, v101, s13, v13
	v_lshl_add_u64 v[12:13], v[12:13], 0, v[176:177]
	v_lshl_add_u64 v[14:15], s[4:5], 0, v[14:15]
	v_lshl_add_u64 v[84:85], v[12:13], 0, v[40:41]
	v_or_b32_e32 v12, 4, v8
	v_mov_b32_e32 v13, v101
	global_load_dwordx4 v[88:91], v[56:57], off offset:32
	global_load_dwordx4 v[92:95], v[56:57], off offset:16
	global_load_dwordx4 v[68:71], v[14:15], off offset:48
	global_load_dwordx4 v[72:75], v[14:15], off offset:32
	global_load_dwordx4 v[76:79], v[14:15], off offset:16
	global_load_dwordx4 v[80:83], v[14:15], off
	v_lshlrev_b64 v[14:15], 6, v[12:13]
	v_mad_u64_u32 v[12:13], s[2:3], v12, s13, v[4:5]
	v_mad_i32_i24 v13, v101, s13, v13
	v_lshl_add_u64 v[12:13], v[12:13], 0, v[176:177]
	v_lshl_add_u64 v[156:157], v[12:13], 0, v[40:41]
	v_or_b32_e32 v12, 5, v8
	v_mov_b32_e32 v13, v101
	v_lshl_add_u64 v[86:87], s[4:5], 0, v[14:15]
	v_lshlrev_b64 v[14:15], 6, v[12:13]
	v_mad_u64_u32 v[12:13], s[2:3], v12, s13, v[4:5]
	v_mad_i32_i24 v13, v101, s13, v13
	v_lshl_add_u64 v[12:13], v[12:13], 0, v[176:177]
	v_lshl_add_u64 v[14:15], s[4:5], 0, v[14:15]
	v_lshl_add_u64 v[160:161], v[12:13], 0, v[40:41]
	v_or_b32_e32 v12, 6, v8
	v_mov_b32_e32 v13, v101
	v_mad_u64_u32 v[10:11], s[2:3], v8, s13, v[4:5]
	global_load_dwordx4 v[60:63], v[86:87], off offset:32
	global_load_dwordx4 v[64:67], v[86:87], off offset:16
	global_load_dwordx4 v[36:39], v[14:15], off offset:48
	global_load_dwordx4 v[44:47], v[14:15], off offset:32
	global_load_dwordx4 v[48:51], v[14:15], off offset:16
	global_load_dwordx4 v[52:55], v[14:15], off
	v_lshlrev_b64 v[14:15], 6, v[12:13]
	v_mad_u64_u32 v[12:13], s[2:3], v12, s13, v[4:5]
	v_or_b32_e32 v8, 7, v8
	v_mad_i32_i24 v13, v101, s13, v13
	v_mad_u64_u32 v[4:5], s[2:3], v8, s13, v[4:5]
	v_mad_i32_i24 v11, v101, s13, v11
	v_lshl_add_u64 v[12:13], v[12:13], 0, v[176:177]
	v_mad_i32_i24 v5, v101, s13, v5
	s_movk_i32 s2, 0x1000
	v_lshl_add_u64 v[10:11], v[10:11], 0, v[176:177]
	v_lshl_add_u64 v[164:165], v[12:13], 0, v[40:41]
	v_lshlrev_b64 v[12:13], 6, v[8:9]
	v_lshl_add_u64 v[4:5], v[4:5], 0, v[176:177]
	v_add_co_u32_e32 v6, vcc, s2, v6
	v_lshl_add_u64 v[10:11], v[10:11], 0, v[40:41]
	v_lshl_add_u64 v[162:163], s[4:5], 0, v[14:15]
	v_lshl_add_u64 v[24:25], s[4:5], 0, v[12:13]
	v_lshl_add_u64 v[4:5], v[4:5], 0, v[40:41]
	v_addc_co_u32_e32 v7, vcc, 0, v7, vcc
	global_load_dwordx4 v[28:31], v[162:163], off offset:32
	global_load_dwordx4 v[32:35], v[162:163], off offset:16
	global_load_dwordx4 v[12:15], v[24:25], off offset:48
	global_load_dwordx4 v[16:19], v[24:25], off offset:32
	global_load_dwordx4 v[20:23], v[24:25], off offset:16
	s_nop 0
	global_load_dwordx4 v[24:27], v[24:25], off
	s_nop 0
	global_load_dwordx4 v[142:145], v[154:155], off offset:48
	global_load_ushort v168, v[10:11], off offset:3840
	global_load_dwordx4 v[146:149], v[56:57], off
	global_load_ushort v169, v[42:43], off offset:3840
	global_load_dwordx4 v[150:153], v[56:57], off offset:48
	global_load_ushort v170, v[58:59], off offset:3840
	global_load_dwordx4 v[96:99], v[86:87], off
	global_load_ushort v171, v[84:85], off offset:3840
	s_nop 0
	global_load_dwordx4 v[84:87], v[86:87], off offset:48
	s_nop 0
	global_load_ushort v172, v[156:157], off offset:3840
	global_load_dwordx4 v[56:59], v[162:163], off
	global_load_ushort v173, v[160:161], off offset:3840
	global_load_dwordx4 v[40:43], v[162:163], off offset:48
	s_nop 0
	global_load_ushort v162, v[164:165], off offset:3840
	global_load_ushort v163, v[4:5], off offset:3840
	global_load_dwordx4 v[8:11], v[6:7], off
	s_nop 0
	global_load_dwordx4 v[154:157], v[154:155], off
	s_nop 0
	global_load_dwordx4 v[4:7], v[158:159], off offset:16
	v_lshl_add_u64 v[158:159], s[82:83], 0, v[104:105]
	v_lshlrev_b32_e32 v104, 2, v166
	v_or3_b32 v160, v109, s8, v166
	v_lshl_add_u64 v[158:159], v[158:159], 0, v[104:105]
	v_ashrrev_i32_e32 v161, 31, v160
	global_load_dword v164, v[158:159], off
	global_load_dword v165, v[158:159], off offset:512
	global_load_dword v174, v[158:159], off offset:1024
	global_load_dword v175, v[158:159], off offset:1536
	global_load_dword v186, v[158:159], off offset:2048
	global_load_dword v187, v[158:159], off offset:2560
	global_load_dword v188, v[158:159], off offset:3072
	global_load_dword v189, v[158:159], off offset:3584
	v_add_co_u32_e32 v158, vcc, s2, v158
	v_lshl_add_u64 v[160:161], v[160:161], 2, s[50:51]
	s_nop 0
	v_addc_co_u32_e32 v159, vcc, 0, v159, vcc
	global_load_dword v160, v[160:161], off
	s_nop 0
	global_load_dword v161, v[158:159], off offset:512
	global_load_dword v190, v[158:159], off offset:1024
	global_load_dword v191, v[158:159], off offset:1536
	global_load_dword v192, v[158:159], off offset:2048
	global_load_dword v193, v[158:159], off offset:2560
	global_load_dword v194, v[158:159], off offset:3072
	global_load_dword v195, v[158:159], off offset:3584
	s_nop 0
	global_load_dword v158, v[158:159], off
	s_waitcnt vmcnt(0)
	s_barrier
	s_mov_b32 s3, 0xbfb8aa3b
	s_mov_b32 s2, 0x3d800000
	v_cmp_gt_u32_sdwa s[4:5], v115, v219 src0_sel:BYTE_0 src1_sel:DWORD
	s_waitcnt vmcnt(15)
	v_mul_f32_e32 v105, v155, v165
	v_fmac_f32_e32 v105, v154, v164
	s_waitcnt vmcnt(14)
	v_fmac_f32_e32 v105, v156, v174
	s_waitcnt vmcnt(13)
	v_fmac_f32_e32 v105, v157, v175
	s_waitcnt vmcnt(12)
	v_fmac_f32_e32 v105, v122, v186
	s_waitcnt vmcnt(7)
	v_mul_f32_e32 v119, v119, v161
	v_fmac_f32_e32 v105, v123, v187
	v_mul_f32_e32 v81, v81, v165
	v_fmac_f32_e32 v105, v124, v188
	v_fmac_f32_e32 v81, v80, v164
	v_mul_f32_e32 v73, v73, v161
	v_fmac_f32_e32 v105, v125, v189
	s_waitcnt vmcnt(0)
	v_fmac_f32_e32 v119, v118, v158
	v_fmac_f32_e32 v119, v120, v190
	v_fmac_f32_e32 v119, v121, v191
	v_fmac_f32_e32 v119, v142, v192
	v_fmac_f32_e32 v119, v143, v193
	v_fmac_f32_e32 v119, v144, v194
	v_fmac_f32_e32 v81, v82, v174
	v_fmac_f32_e32 v73, v72, v158
	v_mul_f32_e32 v53, v53, v165
	v_add_f32_e32 v105, v105, v160
	v_fmac_f32_e32 v119, v145, v195
	v_fmac_f32_e32 v81, v83, v175
	v_fmac_f32_e32 v73, v74, v190
	v_fmac_f32_e32 v53, v52, v164
	v_mul_f32_e32 v45, v45, v161
	v_add_f32_e32 v118, v119, v105
	v_fmac_f32_e32 v81, v76, v186
	v_fmac_f32_e32 v73, v75, v191
	v_fmac_f32_e32 v53, v54, v174
	v_fmac_f32_e32 v45, v44, v158
	v_mul_f32_e64 v105, |v118|, s3
	v_fmac_f32_e32 v81, v77, v187
	v_fmac_f32_e32 v73, v68, v192
	v_fmac_f32_e32 v53, v55, v175
	v_fmac_f32_e32 v45, v46, v190
	v_exp_f32_e32 v105, v105
	v_fmac_f32_e32 v81, v78, v188
	v_fmac_f32_e32 v73, v69, v193
	v_fmac_f32_e32 v53, v48, v186
	v_fmac_f32_e32 v45, v47, v191
	v_fmac_f32_e32 v81, v79, v189
	v_fmac_f32_e32 v73, v70, v194
	v_fmac_f32_e32 v53, v49, v187
	v_fmac_f32_e32 v45, v36, v192
	v_mul_f32_e32 v121, v139, v165
	v_add_f32_e32 v76, v81, v160
	v_fmac_f32_e32 v73, v71, v195
	v_fmac_f32_e32 v53, v50, v188
	v_fmac_f32_e32 v45, v37, v193
	v_fmac_f32_e32 v121, v138, v164
	v_mul_f32_e32 v122, v131, v161
	v_add_f32_e32 v68, v73, v76
	v_fmac_f32_e32 v53, v51, v189
	v_fmac_f32_e32 v45, v38, v194
	v_add_f32_e32 v105, 1.0, v105
	v_fmac_f32_e32 v121, v140, v174
	v_fmac_f32_e32 v122, v130, v158
	v_mul_f32_e64 v69, |v68|, s3
	v_add_f32_e32 v48, v53, v160
	v_fmac_f32_e32 v45, v39, v195
	v_log_f32_e32 v120, v105
	v_fmac_f32_e32 v121, v141, v175
	v_fmac_f32_e32 v122, v132, v190
	v_exp_f32_e32 v69, v69
	v_add_f32_e32 v36, v45, v48
	v_fmac_f32_e32 v121, v134, v186
	v_fmac_f32_e32 v122, v133, v191
	v_mul_f32_e64 v37, |v36|, s3
	v_fmac_f32_e32 v121, v135, v187
	v_fmac_f32_e32 v122, v126, v192
	v_exp_f32_e32 v37, v37
	v_min_f32_e32 v118, 0, v118
	v_fmac_f32_e32 v121, v136, v188
	v_fmac_f32_e32 v122, v127, v193
	v_fmac_f32_e32 v118, 0xbf317218, v120
	v_fmac_f32_e32 v121, v137, v189
	v_fmac_f32_e32 v122, v128, v194
	v_mul_u32_u24_e32 v123, 0x108, v103
	v_add_f32_e32 v69, 1.0, v69
	v_lshrrev_b32_e32 v119, 8, v106
	v_add_f32_e32 v121, v121, v160
	v_fmac_f32_e32 v122, v129, v195
	v_fma_f32 v118, v118, s2, 0
	v_add_lshl_u32 v123, v123, v166, 2
	s_mov_b32 s2, 0xd800
	v_log_f32_e32 v69, v69
	v_lshlrev_b32_e32 v120, 16, v168
	v_add_f32_e32 v121, v122, v121
	v_mad_i32_i24 v123, v119, s2, v123
	v_add_f32_e32 v37, 1.0, v37
	v_mul_f32_e64 v122, |v121|, s3
	ds_write2st64_b32 v123, v118, v120 offset1:68
	v_min_f32_e32 v120, 0, v121
	v_mul_f32_e32 v121, v147, v165
	v_log_f32_e32 v37, v37
	v_fmac_f32_e32 v121, v146, v164
	v_mul_f32_e32 v89, v89, v161
	v_min_f32_e32 v68, 0, v68
	v_fmac_f32_e32 v121, v148, v174
	v_fmac_f32_e32 v89, v88, v158
	v_fmac_f32_e32 v68, 0xbf317218, v69
	v_mul_f32_e32 v69, v97, v165
	v_fmac_f32_e32 v121, v149, v175
	v_fmac_f32_e32 v89, v90, v190
	v_fmac_f32_e32 v69, v96, v164
	v_mul_f32_e32 v61, v61, v161
	v_min_f32_e32 v36, 0, v36
	v_fmac_f32_e32 v121, v92, v186
	v_fmac_f32_e32 v89, v91, v191
	v_fmac_f32_e32 v69, v98, v174
	v_fmac_f32_e32 v61, v60, v158
	v_fmac_f32_e32 v36, 0xbf317218, v37
	v_mul_f32_e32 v37, v57, v165
	v_fmac_f32_e32 v121, v93, v187
	v_fmac_f32_e32 v89, v150, v192
	v_fmac_f32_e32 v69, v99, v175
	v_fmac_f32_e32 v61, v62, v190
	v_fmac_f32_e32 v37, v56, v164
	v_mul_f32_e32 v29, v29, v161
	v_mul_f32_e32 v25, v25, v165
	v_fmac_f32_e32 v121, v94, v188
	v_fmac_f32_e32 v89, v151, v193
	v_fmac_f32_e32 v69, v64, v186
	v_fmac_f32_e32 v61, v63, v191
	v_fmac_f32_e32 v37, v58, v174
	v_fmac_f32_e32 v29, v28, v158
	v_fmac_f32_e32 v25, v24, v164
	v_mul_f32_e32 v17, v17, v161
	v_fmac_f32_e32 v121, v95, v189
	v_fmac_f32_e32 v89, v152, v194
	v_fmac_f32_e32 v69, v65, v187
	v_fmac_f32_e32 v61, v84, v192
	v_fmac_f32_e32 v37, v59, v175
	v_fmac_f32_e32 v29, v30, v190
	v_fmac_f32_e32 v25, v26, v174
	v_fmac_f32_e32 v17, v16, v158
	v_add_f32_e32 v92, v121, v160
	v_fmac_f32_e32 v89, v153, v195
	v_fmac_f32_e32 v69, v66, v188
	v_fmac_f32_e32 v61, v85, v193
	v_fmac_f32_e32 v37, v32, v186
	v_fmac_f32_e32 v29, v31, v191
	v_fmac_f32_e32 v25, v27, v175
	v_fmac_f32_e32 v17, v18, v190
	v_add_f32_e32 v88, v89, v92
	v_fmac_f32_e32 v69, v67, v189
	v_fmac_f32_e32 v61, v86, v194
	v_fmac_f32_e32 v37, v33, v187
	v_fmac_f32_e32 v29, v40, v192
	v_fmac_f32_e32 v25, v20, v186
	v_fmac_f32_e32 v17, v19, v191
	v_exp_f32_e32 v122, v122
	v_mul_f32_e64 v89, |v88|, s3
	v_add_f32_e32 v64, v69, v160
	v_fmac_f32_e32 v61, v87, v195
	v_fmac_f32_e32 v37, v34, v188
	v_fmac_f32_e32 v29, v41, v193
	v_fmac_f32_e32 v25, v21, v187
	v_fmac_f32_e32 v17, v12, v192
	v_exp_f32_e32 v89, v89
	v_add_f32_e32 v60, v61, v64
	v_fmac_f32_e32 v37, v35, v189
	v_fmac_f32_e32 v29, v42, v194
	v_fmac_f32_e32 v25, v22, v188
	v_fmac_f32_e32 v17, v13, v193
	v_mul_f32_e64 v61, |v60|, s3
	v_add_f32_e32 v32, v37, v160
	v_fmac_f32_e32 v29, v43, v195
	v_fmac_f32_e32 v25, v23, v189
	v_fmac_f32_e32 v17, v14, v194
	v_exp_f32_e32 v61, v61
	v_add_f32_e32 v28, v29, v32
	v_add_f32_e32 v20, v25, v160
	v_fmac_f32_e32 v17, v15, v195
	v_add_f32_e32 v122, 1.0, v122
	v_mul_f32_e64 v29, |v28|, s3
	v_add_f32_e32 v12, v17, v20
	v_log_f32_e32 v122, v122
	v_add_f32_e32 v89, 1.0, v89
	v_exp_f32_e32 v29, v29
	v_mul_f32_e64 v13, |v12|, s3
	v_log_f32_e32 v89, v89
	v_exp_f32_e32 v13, v13
	v_add_f32_e32 v61, 1.0, v61
	v_log_f32_e32 v61, v61
	v_fmac_f32_e32 v120, 0xbf317218, v122
	v_mul_u32_u24_e32 v91, 33, v167
	v_min_f32_e32 v88, 0, v88
	v_add_f32_e32 v29, 1.0, v29
	v_fmac_f32_e32 v118, 0x3d800000, v120
	v_add_lshl_u32 v91, v91, v166, 2
	v_fmac_f32_e32 v88, 0xbf317218, v89
	v_log_f32_e32 v29, v29
	v_add_f32_e32 v13, 1.0, v13
	v_mad_i32_i24 v91, v119, s2, v91
	v_fmamk_f32 v71, v88, 0x3d800000, v118
	v_min_f32_e32 v60, 0, v60
	v_log_f32_e32 v13, v13
	ds_write2_b32 v91, v118, v71 offset1:33
	v_fmac_f32_e32 v71, 0x3d800000, v68
	v_fmac_f32_e32 v60, 0xbf317218, v61
	v_lshlrev_b32_e32 v90, 16, v169
	v_lshlrev_b32_e32 v70, 16, v170
	v_add_u32_e32 v72, 0x4400, v91
	v_fmamk_f32 v39, v60, 0x3d800000, v71
	v_min_f32_e32 v28, 0, v28
	ds_write2_b32 v72, v90, v70 offset1:33
	v_lshlrev_b32_e32 v62, 16, v171
	v_lshlrev_b32_e32 v38, 16, v172
	ds_write2_b32 v91, v71, v39 offset0:66 offset1:99
	ds_write2_b32 v72, v62, v38 offset0:66 offset1:99
	v_fmac_f32_e32 v39, 0x3d800000, v36
	v_fmac_f32_e32 v28, 0xbf317218, v29
	v_min_f32_e32 v12, 0, v12
	v_fmamk_f32 v15, v28, 0x3d800000, v39
	v_fmac_f32_e32 v12, 0xbf317218, v13
	v_mul_i32_i24_e32 v105, 0xd800, v119
	v_lshlrev_b32_e32 v30, 16, v173
	v_lshlrev_b32_e32 v14, 16, v162
	ds_write2_b32 v91, v39, v15 offset0:132 offset1:165
	ds_write2_b32 v72, v30, v14 offset0:132 offset1:165
	v_fmac_f32_e32 v15, 0x3d800000, v12
	v_lshlrev_b32_e32 v12, 8, v103
	v_or3_b32 v12, v105, v12, v104
	v_lshlrev_b32_e32 v13, 16, v163
	ds_write_b32 v91, v15 offset:792
	ds_write_b32 v91, v13 offset:18200
	ds_write_b32 v12, v15 offset:53248
	v_mul_u32_u24_e32 v12, 0x48, v117
	v_lshlrev_b32_e32 v12, 1, v12
	v_mad_i32_i24 v12, v119, s2, v12
	v_mov_b32_e32 v106, 0
	v_lshl_or_b32 v12, v116, 1, v12
	ds_write_b16 v12, v8 offset:34816
	ds_write_b16_d16_hi v12, v8 offset:34960
	ds_write_b16 v12, v9 offset:35104
	ds_write_b16_d16_hi v12, v9 offset:35248
	ds_write_b16 v12, v10 offset:35392
	ds_write_b16_d16_hi v12, v10 offset:35536
	ds_write_b16 v12, v11 offset:35680
	ds_write_b16_d16_hi v12, v11 offset:35824
	ds_write_b16 v12, v4 offset:35968
	ds_write_b16_d16_hi v12, v4 offset:36112
	ds_write_b16 v12, v5 offset:36256
	ds_write_b16_d16_hi v12, v5 offset:36400
	ds_write_b16 v12, v6 offset:36544
	ds_write_b16_d16_hi v12, v6 offset:36688
	ds_write_b16 v12, v7 offset:36832
	ds_write_b16_d16_hi v12, v7 offset:36976
	s_waitcnt lgkmcnt(0)
	s_barrier
	s_and_saveexec_b64 s[2:3], s[4:5]
	s_cbranch_execz .LBB0_196
	s_mov_b32 s4, 0xd000
	v_add3_u32 v4, v105, v104, s4
	v_mov_b32_e32 v106, 0
	ds_read_b32 v220, v4
	ds_read_b32 v221, v4 offset:256
	ds_read_b32 v222, v4 offset:512
	ds_read_b32 v223, v4 offset:768
	ds_read_b32 v224, v4 offset:1024
	ds_read_b32 v225, v4 offset:1280
	ds_read_b32 v226, v4 offset:1536
	s_waitcnt lgkmcnt(0)
	v_add_f32_e32 v106, v106, v220
	v_cmp_lt_u32_e32 vcc, 1, v103
	s_nop 1
	v_cndmask_b32_e32 v221, 0, v221, vcc
	v_add_f32_e32 v106, v106, v221
	v_cmp_lt_u32_e32 vcc, 2, v103
	s_nop 1
	v_cndmask_b32_e32 v222, 0, v222, vcc
	v_add_f32_e32 v106, v106, v222
	v_cmp_lt_u32_e32 vcc, 3, v103
	s_nop 1
	v_cndmask_b32_e32 v223, 0, v223, vcc
	v_add_f32_e32 v106, v106, v223
	v_cmp_lt_u32_e32 vcc, 4, v103
	s_nop 1
	v_cndmask_b32_e32 v224, 0, v224, vcc
	v_add_f32_e32 v106, v106, v224
	v_cmp_lt_u32_e32 vcc, 5, v103
	s_nop 1
	v_cndmask_b32_e32 v225, 0, v225, vcc
	v_add_f32_e32 v106, v106, v225
	v_cmp_lt_u32_e32 vcc, 6, v103
	s_nop 1
	v_cndmask_b32_e32 v226, 0, v226, vcc
	v_add_f32_e32 v106, v106, v226
	v_mov_b32_e32 v103, 0
.LBB0_196:
	s_or_b64 exec, exec, s[2:3]
	v_mul_u32_u24_e32 v4, 0x84, v114
	v_add3_u32 v6, v105, v104, v4
	ds_read2_b32 v[228:229], v6 offset1:33
	ds_read2_b32 v[230:231], v6 offset0:66 offset1:99
	ds_read2_b32 v[232:233], v6 offset0:132 offset1:165
	ds_read2_b32 v[234:235], v6 offset0:198 offset1:231
	s_movk_i32 s2, 0x90
	v_bfe_u32 v7, v111, 5, 3
	v_lshlrev_b32_e32 v8, 4, v7
	v_mul_u32_u24_e32 v7, 0x420, v7
	v_lshlrev_b32_e32 v15, 3, v112
	s_waitcnt lgkmcnt(0)
	v_pk_add_f32 v[228:229], v[106:107], v[228:229] op_sel_hi:[0,1]
	v_pk_add_f32 v[230:231], v[106:107], v[230:231] op_sel_hi:[0,1]
	v_pk_add_f32 v[232:233], v[106:107], v[232:233] op_sel_hi:[0,1]
	v_pk_add_f32 v[234:235], v[106:107], v[234:235] op_sel_hi:[0,1]
	ds_write2_b32 v6, v228, v229 offset1:33
	ds_write2_b32 v6, v230, v231 offset0:66 offset1:99
	ds_write2_b32 v6, v232, v233 offset0:132 offset1:165
	ds_write2_b32 v6, v234, v235 offset0:198 offset1:231
	v_and_b32_e32 v5, 31, v111
	v_lshlrev_b32_e32 v6, 2, v5
	v_add_u32_e32 v4, v105, v6
	s_waitcnt lgkmcnt(0)
	s_barrier
	ds_read_b32 v4, v4 offset:8316
	v_mad_u32_u24 v5, v5, s2, v105
	s_mov_b32 s2, 0xac00
	v_add3_u32 v5, v5, v8, s2
	v_add3_u32 v6, v105, v7, v6
	v_add_u32_e32 v199, 0x210, v6
	v_add_u32_e32 v200, 0x4400, v6
	v_add_u32_e32 v201, 0x4610, v6
	ds_read2_b32 v[236:237], v200 offset1:33
	ds_read2_b32 v[238:239], v6 offset1:33
	ds_read2_b32 v[240:241], v200 offset0:66 offset1:99
	ds_read2_b32 v[242:243], v6 offset0:66 offset1:99
	ds_read2_b32 v[244:245], v201 offset1:33
	ds_read2_b32 v[246:247], v199 offset1:33
	ds_read2_b32 v[248:249], v201 offset0:66 offset1:99
	ds_read2_b32 v[250:251], v199 offset0:66 offset1:99
	s_waitcnt lgkmcnt(0)
	v_sub_f32_e32 v238, v4, v238
	v_sub_f32_e32 v239, v4, v239
	v_sub_f32_e32 v242, v4, v242
	v_sub_f32_e32 v243, v4, v243
	v_mul_f32_e32 v238, 0x3fb8aa3b, v238
	v_mul_f32_e32 v239, 0x3fb8aa3b, v239
	v_mul_f32_e32 v242, 0x3fb8aa3b, v242
	v_mul_f32_e32 v243, 0x3fb8aa3b, v243
	v_exp_f32_e32 v238, v238
	v_exp_f32_e32 v239, v239
	v_exp_f32_e32 v242, v242
	v_exp_f32_e32 v243, v243
	s_nop 0
	v_mul_f32_e32 v238, v236, v238
	v_mul_f32_e32 v239, v237, v239
	v_mul_f32_e32 v242, v240, v242
	v_mul_f32_e32 v243, v241, v243
	v_cvt_pk_bf16_f32 v236, v238, v239
	v_cvt_pk_bf16_f32 v237, v242, v243
	ds_write_b64 v5, v[236:237]
	v_sub_f32_e32 v246, v4, v246
	v_sub_f32_e32 v247, v4, v247
	v_sub_f32_e32 v250, v4, v250
	v_sub_f32_e32 v251, v4, v251
	v_mul_f32_e32 v246, 0x3fb8aa3b, v246
	v_mul_f32_e32 v247, 0x3fb8aa3b, v247
	v_mul_f32_e32 v250, 0x3fb8aa3b, v250
	v_mul_f32_e32 v251, 0x3fb8aa3b, v251
	v_exp_f32_e32 v246, v246
	v_exp_f32_e32 v247, v247
	v_exp_f32_e32 v250, v250
	v_exp_f32_e32 v251, v251
	s_nop 0
	v_mul_f32_e32 v246, v244, v246
	v_mul_f32_e32 v247, v245, v247
	v_mul_f32_e32 v250, v248, v250
	v_mul_f32_e32 v251, v249, v251
	v_cvt_pk_bf16_f32 v244, v246, v247
	v_cvt_pk_bf16_f32 v245, v250, v251
	ds_write_b64 v5, v[244:245] offset:8
	v_lshl_add_u32 v8, v15, 1, v105
	s_movk_i32 s2, 0x90
	v_mad_u32_u24 v12, v110, s2, v8
	s_waitcnt lgkmcnt(0)
	s_barrier
	ds_read_b128 v[4:7], v12 offset:34816
	v_mad_u32_u24 v13, v107, s2, v8
	ds_read_b128 v[8:11], v13 offset:44032
	ds_read_b128 v[16:19], v13 offset:46336
	ds_read_b128 v[20:23], v12 offset:34880
	ds_read_b128 v[24:27], v13 offset:46400
	s_waitcnt lgkmcnt(3)
	v_mfma_f32_16x16x32_bf16 v[8:11], v[8:11], v[4:7], 0
	v_ashrrev_i32_e32 v103, 31, v102
	v_readlane_b32 s2, v254, 17
	v_readlane_b32 s3, v254, 18
	s_waitcnt lgkmcnt(2)
	v_mfma_f32_16x16x32_bf16 v[4:7], v[16:19], v[4:7], 0
	ds_read_b128 v[16:19], v13 offset:44096
	v_mov_b32_e32 v13, v177
	v_cmp_lt_u32_sdwa s[4:5], v111, v218 src0_sel:BYTE_0 src1_sel:DWORD
	s_waitcnt lgkmcnt(1)
	v_mfma_f32_16x16x32_bf16 v[4:7], v[24:27], v[20:23], v[4:7]
	v_lshlrev_b32_e32 v24, 2, v112
	s_waitcnt lgkmcnt(0)
	v_mfma_f32_16x16x32_bf16 v[16:19], v[16:19], v[20:23], v[8:11]
	s_nop 2
	v_or_b32_e32 v198, v113, v107
	v_lshl_or_b32 v198, v198, 5, v24
	v_lshlrev_b32_e32 v196, 2, v198
	v_mov_b32_e32 v197, v177
	v_or_b32_e32 v11, v113, v24
	v_lshlrev_b32_e32 v11, 5, v11
	v_lshlrev_b64 v[8:9], 13, v[102:103]
	v_or_b32_e32 v12, v11, v107
	v_lshl_add_u64 v[8:9], s[2:3], 0, v[8:9]
	v_lshl_add_u64 v[196:197], v[8:9], 0, v[196:197]
	v_lshlrev_b32_e32 v12, 2, v12
	v_or_b32_e32 v10, 16, v107
	v_lshl_add_u64 v[12:13], v[8:9], 0, v[12:13]
	global_store_dwordx4 v[196:197], v[16:19], off sc1
	global_store_dwordx4 v[196:197], v[4:7], off offset:64 sc1
	s_nop 1
	v_or_b32_e32 v4, v11, v10
	v_lshlrev_b32_e32 v12, 2, v4
	v_mov_b32_e32 v13, v177
	v_lshl_add_u64 v[8:9], v[8:9], 0, v[12:13]
	s_and_saveexec_b64 s[2:3], s[4:5]
	s_cbranch_execz .LBB0_200
	v_lshlrev_b32_sdwa v4, v213, v111 dst_sel:DWORD dst_unused:UNUSED_PAD src0_sel:DWORD src1_sel:BYTE_0
	v_add_u32_e32 v5, v105, v4
	ds_read_b32 v5, v5 offset:8316
	v_readlane_b32 s4, v254, 19
	v_lshlrev_b64 v[6:7], 7, v[102:103]
	v_readlane_b32 s5, v254, 20
	s_waitcnt lgkmcnt(0)
	v_mul_f32_e32 v5, 0x3fb8aa3b, v5
	v_exp_f32_e32 v8, v5
	v_lshl_add_u64 v[6:7], s[4:5], 0, v[6:7]
	v_mov_b32_e32 v5, v177
	v_lshl_add_u64 v[4:5], v[6:7], 0, v[4:5]
	global_store_dword v[4:5], v8, off

.LBB0_238:
	s_or_b64 exec, exec, s[2:3]
	v_lshlrev_b32_e32 v29, 3, v23
	v_lshl_add_u32 v8, v21, 2, v28
	v_mov_b32_e32 v21, v20
	v_mad_u32_u24 v30, v18, s14, v8
	ds_read_b32 v80, v30
	ds_read_b32 v81, v30 offset:260
	ds_read_b32 v82, v30 offset:520
	ds_read_b32 v83, v30 offset:780
	ds_read_b32 v84, v30 offset:1040
	ds_read_b32 v85, v30 offset:1300
	ds_read_b32 v86, v30 offset:1560
	ds_read_b32 v87, v30 offset:1820
	ds_read_b32 v88, v30 offset:2080
	ds_read_b32 v89, v30 offset:2340
	ds_read_b32 v90, v30 offset:2600
	ds_read_b32 v91, v30 offset:2860
	ds_read_b32 v92, v30 offset:3120
	ds_read_b32 v93, v30 offset:3380
	ds_read_b32 v94, v30 offset:3640
	ds_read_b32 v95, v30 offset:3900
	s_waitcnt lgkmcnt(0)
	v_add_f32_e32 v80, v20, v80
	v_add_f32_e32 v81, v20, v81
	v_add_f32_e32 v82, v20, v82
	v_add_f32_e32 v83, v20, v83
	v_add_f32_e32 v84, v20, v84
	v_add_f32_e32 v85, v20, v85
	v_add_f32_e32 v86, v20, v86
	v_add_f32_e32 v87, v20, v87
	v_add_f32_e32 v88, v20, v88
	v_add_f32_e32 v89, v20, v89
	v_add_f32_e32 v90, v20, v90
	v_add_f32_e32 v91, v20, v91
	v_add_f32_e32 v92, v20, v92
	v_add_f32_e32 v93, v20, v93
	v_add_f32_e32 v94, v20, v94
	v_add_f32_e32 v95, v20, v95
	ds_write_b32 v30, v80
	ds_write_b32 v30, v81 offset:260
	ds_write_b32 v30, v82 offset:520
	ds_write_b32 v30, v83 offset:780
	ds_write_b32 v30, v84 offset:1040
	ds_write_b32 v30, v85 offset:1300
	ds_write_b32 v30, v86 offset:1560
	ds_write_b32 v30, v87 offset:1820
	ds_write_b32 v30, v88 offset:2080
	ds_write_b32 v30, v89 offset:2340
	ds_write_b32 v30, v90 offset:2600
	ds_write_b32 v30, v91 offset:2860
	ds_write_b32 v30, v92 offset:3120
	ds_write_b32 v30, v93 offset:3380
	ds_write_b32 v30, v94 offset:3640
	ds_write_b32 v30, v95 offset:3900
	v_and_b32_e32 v9, 63, v22
	v_lshlrev_b32_e32 v10, 2, v9
	v_add_u32_e32 v8, v28, v10
	s_waitcnt lgkmcnt(0)
	s_barrier
	ds_read_b32 v8, v8 offset:16380
	s_movk_i32 s2, 0x90
	v_mad_u32_u24 v9, v9, s2, v28
	v_lshlrev_b32_e32 v11, 5, v17
	s_mov_b32 s2, 0xac00
	v_add3_u32 v9, v9, v11, s2
	v_mul_u32_u24_e32 v11, 0x1040, v17
	v_add3_u32 v10, v28, v11, v10
	v_add_u32_e32 v72, 0x410, v10
	v_add_u32_e32 v73, 0x820, v10
	v_add_u32_e32 v74, 0xc30, v10
	v_add_u32_e32 v76, 0x4400, v10
	v_add_u32_e32 v77, 0x4810, v10
	v_add_u32_e32 v78, 0x4c20, v10
	v_add_u32_e32 v79, 0x5030, v10
	ds_read2_b32 v[96:97], v76 offset1:65
	ds_read2_b32 v[98:99], v10 offset1:65
	ds_read2_b32 v[100:101], v76 offset0:130 offset1:195
	ds_read2_b32 v[102:103], v10 offset0:130 offset1:195
	ds_read2_b32 v[104:105], v77 offset1:65
	ds_read2_b32 v[106:107], v72 offset1:65
	ds_read2_b32 v[108:109], v77 offset0:130 offset1:195
	ds_read2_b32 v[110:111], v72 offset0:130 offset1:195
	ds_read2_b32 v[112:113], v78 offset1:65
	ds_read2_b32 v[114:115], v73 offset1:65
	ds_read2_b32 v[116:117], v78 offset0:130 offset1:195
	ds_read2_b32 v[118:119], v73 offset0:130 offset1:195
	ds_read2_b32 v[120:121], v79 offset1:65
	ds_read2_b32 v[122:123], v74 offset1:65
	ds_read2_b32 v[124:125], v79 offset0:130 offset1:195
	ds_read2_b32 v[126:127], v74 offset0:130 offset1:195
	s_waitcnt lgkmcnt(0)
	v_sub_f32_e32 v98, v8, v98
	v_sub_f32_e32 v99, v8, v99
	v_sub_f32_e32 v102, v8, v102
	v_sub_f32_e32 v103, v8, v103
	v_mul_f32_e32 v98, 0x3fb8aa3b, v98
	v_mul_f32_e32 v99, 0x3fb8aa3b, v99
	v_mul_f32_e32 v102, 0x3fb8aa3b, v102
	v_mul_f32_e32 v103, 0x3fb8aa3b, v103
	v_exp_f32_e32 v98, v98
	v_exp_f32_e32 v99, v99
	v_exp_f32_e32 v102, v102
	v_exp_f32_e32 v103, v103
	s_nop 0
	v_mul_f32_e32 v98, v96, v98
	v_mul_f32_e32 v99, v97, v99
	v_mul_f32_e32 v102, v100, v102
	v_mul_f32_e32 v103, v101, v103
	v_cvt_pk_bf16_f32 v96, v98, v99
	v_cvt_pk_bf16_f32 v97, v102, v103
	ds_write_b64 v9, v[96:97]
	v_sub_f32_e32 v106, v8, v106
	v_sub_f32_e32 v107, v8, v107
	v_sub_f32_e32 v110, v8, v110
	v_sub_f32_e32 v111, v8, v111
	v_mul_f32_e32 v106, 0x3fb8aa3b, v106
	v_mul_f32_e32 v107, 0x3fb8aa3b, v107
	v_mul_f32_e32 v110, 0x3fb8aa3b, v110
	v_mul_f32_e32 v111, 0x3fb8aa3b, v111
	v_exp_f32_e32 v106, v106
	v_exp_f32_e32 v107, v107
	v_exp_f32_e32 v110, v110
	v_exp_f32_e32 v111, v111
	s_nop 0
	v_mul_f32_e32 v106, v104, v106
	v_mul_f32_e32 v107, v105, v107
	v_mul_f32_e32 v110, v108, v110
	v_mul_f32_e32 v111, v109, v111
	v_cvt_pk_bf16_f32 v104, v106, v107
	v_cvt_pk_bf16_f32 v105, v110, v111
	ds_write_b64 v9, v[104:105] offset:8
	v_sub_f32_e32 v114, v8, v114
	v_sub_f32_e32 v115, v8, v115
	v_sub_f32_e32 v118, v8, v118
	v_sub_f32_e32 v119, v8, v119
	v_mul_f32_e32 v114, 0x3fb8aa3b, v114
	v_mul_f32_e32 v115, 0x3fb8aa3b, v115
	v_mul_f32_e32 v118, 0x3fb8aa3b, v118
	v_mul_f32_e32 v119, 0x3fb8aa3b, v119
	v_exp_f32_e32 v114, v114
	v_exp_f32_e32 v115, v115
	v_exp_f32_e32 v118, v118
	v_exp_f32_e32 v119, v119
	s_nop 0
	v_mul_f32_e32 v114, v112, v114
	v_mul_f32_e32 v115, v113, v115
	v_mul_f32_e32 v118, v116, v118
	v_mul_f32_e32 v119, v117, v119
	v_cvt_pk_bf16_f32 v112, v114, v115
	v_cvt_pk_bf16_f32 v113, v118, v119
	ds_write_b64 v9, v[112:113] offset:16
	v_sub_f32_e32 v122, v8, v122
	v_sub_f32_e32 v123, v8, v123
	v_sub_f32_e32 v126, v8, v126
	v_sub_f32_e32 v127, v8, v127
	v_mul_f32_e32 v122, 0x3fb8aa3b, v122
	v_mul_f32_e32 v123, 0x3fb8aa3b, v123
	v_mul_f32_e32 v126, 0x3fb8aa3b, v126
	v_mul_f32_e32 v127, 0x3fb8aa3b, v127
	v_exp_f32_e32 v122, v122
	v_exp_f32_e32 v123, v123
	v_exp_f32_e32 v126, v126
	v_exp_f32_e32 v127, v127
	s_nop 0
	v_mul_f32_e32 v122, v120, v122
	v_mul_f32_e32 v123, v121, v123
	v_mul_f32_e32 v126, v124, v126
	v_mul_f32_e32 v127, v125, v127
	v_cvt_pk_bf16_f32 v120, v122, v123
	v_cvt_pk_bf16_f32 v121, v126, v127
	ds_write_b64 v9, v[120:121] offset:24
	v_lshl_add_u32 v12, v29, 1, v28
	s_movk_i32 s2, 0x90
	v_mad_u32_u24 v17, v19, s2, v12
	s_waitcnt lgkmcnt(0)
	s_barrier
	ds_read_b128 v[8:11], v17 offset:34816
	v_mad_u32_u24 v18, v26, s2, v12
	ds_read_b128 v[12:15], v18 offset:44032
	ds_read_b128 v[34:37], v18 offset:46336
	ds_read_b128 v[38:41], v18 offset:48640
	ds_read_b128 v[42:45], v18 offset:50944
	s_waitcnt lgkmcnt(3)
	v_mfma_f32_16x16x32_bf16 v[12:15], v[12:15], v[8:11], 0
	v_lshlrev_b32_e32 v30, 2, v23
	v_mov_b32_e32 v33, v177
	v_or_b32_e32 v51, 16, v26
	s_waitcnt lgkmcnt(2)
	v_mfma_f32_16x16x32_bf16 v[34:37], v[34:37], v[8:11], 0
	v_or_b32_e32 v48, 32, v26
	v_or_b32_e32 v31, 48, v26
	v_cmp_lt_u32_sdwa s[4:5], v22, v216 src0_sel:BYTE_0 src1_sel:DWORD
	s_waitcnt lgkmcnt(1)
	v_mfma_f32_16x16x32_bf16 v[38:41], v[38:41], v[8:11], 0
	s_waitcnt lgkmcnt(0)
	v_mfma_f32_16x16x32_bf16 v[8:11], v[42:45], v[8:11], 0
	ds_read_b128 v[42:45], v17 offset:34880
	ds_read_b128 v[52:55], v18 offset:44096
	v_ashrrev_i32_e32 v17, 31, v16
	v_lshlrev_b64 v[20:21], 14, v[16:17]
	s_waitcnt lgkmcnt(0)
	v_mfma_f32_16x16x32_bf16 v[12:15], v[52:55], v[42:45], v[12:15]
	ds_read_b128 v[52:55], v18 offset:46400
	v_lshl_add_u64 v[20:21], s[78:79], 0, v[20:21]
	s_waitcnt lgkmcnt(0)
	v_mfma_f32_16x16x32_bf16 v[34:37], v[52:55], v[42:45], v[34:37]
	ds_read_b128 v[52:55], v18 offset:48704
	s_waitcnt lgkmcnt(0)
	v_mfma_f32_16x16x32_bf16 v[38:41], v[52:55], v[42:45], v[38:41]
	ds_read_b128 v[52:55], v18 offset:51008
	v_or_b32_e32 v66, v32, v26
	v_lshl_or_b32 v66, v66, 6, v30
	v_lshlrev_b32_e32 v66, 2, v66
	v_mov_b32_e32 v67, v177
	v_lshl_add_u64 v[66:67], v[20:21], 0, v[66:67]
	v_or_b32_e32 v18, v32, v30
	v_lshlrev_b32_e32 v18, 6, v18
	v_or_b32_e32 v23, v18, v26
	v_lshlrev_b32_e32 v32, 2, v23
	v_lshl_add_u64 v[32:33], v[20:21], 0, v[32:33]
	global_store_dwordx4 v[66:67], v[12:15], off sc1
	global_store_dwordx4 v[66:67], v[34:37], off offset:64 sc1
	global_store_dwordx4 v[66:67], v[38:41], off offset:128 sc1
	s_nop 1
	v_or_b32_e32 v12, v18, v51
	v_lshlrev_b32_e32 v12, 2, v12
	v_mov_b32_e32 v13, v177
	v_lshl_add_u64 v[12:13], v[20:21], 0, v[12:13]
	v_or_b32_e32 v12, v18, v48
	v_lshlrev_b32_e32 v12, 2, v12
	v_mov_b32_e32 v13, v177
	s_waitcnt lgkmcnt(0)
	v_mfma_f32_16x16x32_bf16 v[8:11], v[52:55], v[42:45], v[8:11]
	v_lshl_add_u64 v[12:13], v[20:21], 0, v[12:13]
	s_nop 3
	s_nop 3
	global_store_dwordx4 v[66:67], v[8:11], off offset:192 sc1
	s_nop 1
	v_or_b32_e32 v8, v18, v31
	v_lshlrev_b32_e32 v12, 2, v8
	v_mov_b32_e32 v13, v177
	v_lshl_add_u64 v[12:13], v[20:21], 0, v[12:13]
	s_and_saveexec_b64 s[2:3], s[4:5]
	s_cbranch_execz .LBB0_244
	v_lshlrev_b32_sdwa v8, v213, v22 dst_sel:DWORD dst_unused:UNUSED_PAD src0_sel:DWORD src1_sel:BYTE_0
	v_add_u32_e32 v9, v28, v8
	ds_read_b32 v9, v9 offset:16380
	v_readlane_b32 s4, v254, 21
	v_lshlrev_b64 v[10:11], 8, v[16:17]
	v_readlane_b32 s5, v254, 22
	s_waitcnt lgkmcnt(0)
	v_mul_f32_e32 v9, 0x3fb8aa3b, v9
	v_exp_f32_e32 v12, v9
	v_lshl_add_u64 v[10:11], s[4:5], 0, v[10:11]
	v_mov_b32_e32 v9, v177
	v_lshl_add_u64 v[8:9], v[10:11], 0, v[8:9]
	global_store_dword v[8:9], v12, off
